# v16 + nt (streaming) on the 64 split-K slab stores of the two residual GEMM phases
# baseline (speedup 1.0000x reference)
; template <class Epi, bool ALIGN_EPI = true>
; __device__ __forceinline__ void gemm_phase(LAS unsigned char* lds, const Gemm g, const Order& S, const Epi& E) {
;     ...
;             float* sl = g.slab + (size_t)(cur.slot * cur.S + cur.ks) * 65536 + (size_t)(wr * 64 + fr) * 256 + wc * 32 + 8 * fq;
; #pragma unroll
;             for (int ai = 0; ai < 2; ++ai)
; #pragma unroll
;                 for (int m = 0; m < 4; ++m)
; #pragma unroll
;                     for (int bj = 0; bj < 2; ++bj)
; #pragma unroll
;                         for (int n = 0; n < 2; ++n) *(f32x4*)(sl + (size_t)(ai * HALF + m * 16) * 256 + bj * HALF + 4 * n) = acc[ai][bj][m][n];
.LBB0_245:
	v_readlane_b32 s92, v254, 57
	s_cmp_lg_u32 s35, 0
	v_readlane_b32 s93, v254, 58
	s_mov_b32 s65, s43
	s_cbranch_scc0 .LBB0_247
	s_mul_i32 s34, s35, s34
	s_add_i32 s64, s34, s87
	s_lshl_b64 s[34:35], s[64:65], 18
	v_lshl_add_u64 v[62:63], v[214:215], 0, s[34:35]
	v_add_co_u32_e32 v64, vcc, 0x4000, v62
	global_store_dwordx4 v[62:63], v[174:177], off nt
	global_store_dwordx4 v[62:63], v[170:173], off offset:16 nt
	global_store_dwordx4 v[62:63], v[166:169], off offset:512 nt
	global_store_dwordx4 v[62:63], v[162:165], off offset:528 nt
	v_addc_co_u32_e32 v65, vcc, 0, v63, vcc
	global_store_dwordx4 v[64:65], v[158:161], off nt
	global_store_dwordx4 v[64:65], v[154:157], off offset:16 nt
	global_store_dwordx4 v[64:65], v[150:153], off offset:512 nt
	global_store_dwordx4 v[64:65], v[146:149], off offset:528 nt
	v_add_co_u32_e32 v64, vcc, 0x8000, v62
	s_mov_b32 s28, 0xc000
	s_nop 0
	v_addc_co_u32_e32 v65, vcc, 0, v63, vcc
	global_store_dwordx4 v[64:65], v[142:145], off nt
	global_store_dwordx4 v[64:65], v[138:141], off offset:16 nt
	global_store_dwordx4 v[64:65], v[134:137], off offset:512 nt
	global_store_dwordx4 v[64:65], v[130:133], off offset:528 nt
	v_add_co_u32_e32 v64, vcc, s28, v62
	s_mov_b32 s28, 0x20000
	s_nop 0
	v_addc_co_u32_e32 v65, vcc, 0, v63, vcc
	global_store_dwordx4 v[64:65], v[126:129], off nt
	global_store_dwordx4 v[64:65], v[122:125], off offset:16 nt
	global_store_dwordx4 v[64:65], v[118:121], off offset:512 nt
	global_store_dwordx4 v[64:65], v[114:117], off offset:528 nt
	v_add_co_u32_e32 v64, vcc, s28, v62
	s_mov_b32 s28, 0x24000
	s_nop 0
	v_addc_co_u32_e32 v65, vcc, 0, v63, vcc
	global_store_dwordx4 v[64:65], v[70:73], off nt
	global_store_dwordx4 v[64:65], v[58:61], off offset:16 nt
	global_store_dwordx4 v[64:65], v[54:57], off offset:512 nt
	global_store_dwordx4 v[64:65], v[50:53], off offset:528 nt
	v_add_co_u32_e32 v64, vcc, s28, v62
	s_mov_b64 s[58:59], 0
	s_nop 0
	v_addc_co_u32_e32 v65, vcc, 0, v63, vcc
	global_store_dwordx4 v[64:65], v[46:49], off nt
	global_store_dwordx4 v[64:65], v[42:45], off offset:16 nt
	global_store_dwordx4 v[64:65], v[38:41], off offset:512 nt
	global_store_dwordx4 v[64:65], v[34:37], off offset:528 nt
	v_add_co_u32_e32 v64, vcc, 0x28000, v62
	s_nop 1
	v_addc_co_u32_e32 v65, vcc, 0, v63, vcc
	v_add_co_u32_e32 v62, vcc, 0x2c000, v62
	global_store_dwordx4 v[64:65], v[30:33], off nt
	global_store_dwordx4 v[64:65], v[26:29], off offset:16 nt
	global_store_dwordx4 v[64:65], v[22:25], off offset:512 nt
	global_store_dwordx4 v[64:65], v[18:21], off offset:528 nt
	v_addc_co_u32_e32 v63, vcc, 0, v63, vcc
	global_store_dwordx4 v[62:63], v[14:17], off nt
	global_store_dwordx4 v[62:63], v[10:13], off offset:16 nt
	global_store_dwordx4 v[62:63], v[6:9], off offset:512 nt
	global_store_dwordx4 v[62:63], v[2:5], off offset:528 nt
	s_branch .LBB0_248

; template <class Epi, bool ALIGN_EPI = true>
; __device__ __forceinline__ void gemm_phase(LAS unsigned char* lds, const Gemm g, const Order& S, const Epi& E) {
;     ...
;             float* sl = g.slab + (size_t)(cur.slot * cur.S + cur.ks) * 65536 + (size_t)(wr * 64 + fr) * 256 + wc * 32 + 8 * fq;
; #pragma unroll
;             for (int ai = 0; ai < 2; ++ai)
; #pragma unroll
;                 for (int m = 0; m < 4; ++m)
; #pragma unroll
;                     for (int bj = 0; bj < 2; ++bj)
; #pragma unroll
;                         for (int n = 0; n < 2; ++n) *(f32x4*)(sl + (size_t)(ai * HALF + m * 16) * 256 + bj * HALF + 4 * n) = acc[ai][bj][m][n];
.LBB0_377:
	v_readlane_b32 s92, v254, 57
	s_cmp_lg_u32 s35, 0
	v_readlane_b32 s93, v254, 58
	s_mov_b32 s63, s43
	v_readlane_b32 s90, v255, 22
	s_cbranch_scc0 .LBB0_396
	s_mul_i32 s34, s35, s34
	s_add_i32 s62, s34, s85
	s_lshl_b64 s[34:35], s[62:63], 18
	v_lshl_add_u64 v[62:63], v[214:215], 0, s[34:35]
	v_add_co_u32_e32 v64, vcc, 0x4000, v62
	global_store_dwordx4 v[62:63], v[174:177], off nt
	global_store_dwordx4 v[62:63], v[170:173], off offset:16 nt
	global_store_dwordx4 v[62:63], v[166:169], off offset:512 nt
	global_store_dwordx4 v[62:63], v[162:165], off offset:528 nt
	v_addc_co_u32_e32 v65, vcc, 0, v63, vcc
	global_store_dwordx4 v[64:65], v[158:161], off nt
	global_store_dwordx4 v[64:65], v[154:157], off offset:16 nt
	global_store_dwordx4 v[64:65], v[150:153], off offset:512 nt
	global_store_dwordx4 v[64:65], v[146:149], off offset:528 nt
	v_add_co_u32_e32 v64, vcc, 0x8000, v62
	s_mov_b32 s28, 0xc000
	s_nop 0
	v_addc_co_u32_e32 v65, vcc, 0, v63, vcc
	global_store_dwordx4 v[64:65], v[142:145], off nt
	global_store_dwordx4 v[64:65], v[138:141], off offset:16 nt
	global_store_dwordx4 v[64:65], v[134:137], off offset:512 nt
	global_store_dwordx4 v[64:65], v[130:133], off offset:528 nt
	v_add_co_u32_e32 v64, vcc, s28, v62
	s_mov_b32 s28, 0x20000
	s_nop 0
	v_addc_co_u32_e32 v65, vcc, 0, v63, vcc
	global_store_dwordx4 v[64:65], v[126:129], off nt
	global_store_dwordx4 v[64:65], v[122:125], off offset:16 nt
	global_store_dwordx4 v[64:65], v[118:121], off offset:512 nt
	global_store_dwordx4 v[64:65], v[114:117], off offset:528 nt
	v_add_co_u32_e32 v64, vcc, s28, v62
	s_mov_b32 s28, 0x24000
	s_nop 0
	v_addc_co_u32_e32 v65, vcc, 0, v63, vcc
	global_store_dwordx4 v[64:65], v[70:73], off nt
	global_store_dwordx4 v[64:65], v[58:61], off offset:16 nt
	global_store_dwordx4 v[64:65], v[54:57], off offset:512 nt
	global_store_dwordx4 v[64:65], v[50:53], off offset:528 nt
	v_add_co_u32_e32 v64, vcc, s28, v62
	s_nop 1
	v_addc_co_u32_e32 v65, vcc, 0, v63, vcc
	global_store_dwordx4 v[64:65], v[46:49], off nt
	global_store_dwordx4 v[64:65], v[42:45], off offset:16 nt
	global_store_dwordx4 v[64:65], v[38:41], off offset:512 nt
	global_store_dwordx4 v[64:65], v[34:37], off offset:528 nt
	v_add_co_u32_e32 v64, vcc, 0x28000, v62
	s_nop 1
	v_addc_co_u32_e32 v65, vcc, 0, v63, vcc
	v_add_co_u32_e32 v62, vcc, 0x2c000, v62
	global_store_dwordx4 v[64:65], v[30:33], off nt
	global_store_dwordx4 v[64:65], v[26:29], off offset:16 nt
	global_store_dwordx4 v[64:65], v[22:25], off offset:512 nt
	global_store_dwordx4 v[64:65], v[18:21], off offset:528 nt
	v_addc_co_u32_e32 v63, vcc, 0, v63, vcc
	global_store_dwordx4 v[62:63], v[14:17], off nt
	global_store_dwordx4 v[62:63], v[10:13], off offset:16 nt
	global_store_dwordx4 v[62:63], v[6:9], off offset:512 nt
	global_store_dwordx4 v[62:63], v[2:5], off offset:528 nt
	s_cbranch_execnz .LBB0_397
